# v14 + P3: only wave 0 stores the shared decay-vector LDS row (others skip the redundant ds_write)
# speedup vs baseline: 1.0085x; 1.0037x over previous
.LBB0_173:
	s_cmp_lt_i32 s40, 2
	s_cselect_b64 s[8:9], -1, 0
	s_and_b64 s[12:13], s[8:9], s[6:7]
	s_andn2_b64 vcc, exec, s[12:13]
	s_cbranch_vccnz .LBB0_217
	s_load_dword s32, s[0:1], 0x78
	s_lshr_b32 s100, s2, 4
	s_lshl_b32 s100, s100, 3
	s_and_b32 s101, s2, 7
	s_or_b32 s100, s100, s101
	s_bitcmp1_b32 s2, 3
	s_cselect_b32 s100, s100, 0x100
	s_waitcnt lgkmcnt(0)
	s_cmp_eq_u32 s32, 0x100
	s_cselect_b32 s100, s100, s2
	s_mov_b64 s[6:7], s[0:1]
	s_load_dwordx4 s[8:11], s[6:7], 0x60
	v_lshl_add_u32 v73, s100, 3, v140
	s_movk_i32 s3, 0x800
	v_lshlrev_b32_e32 v0, 4, v73
	v_cmp_gt_i32_e32 vcc, s3, v73
	v_and_b32_e32 v139, 15, v158
	v_mov_b32_e32 v69, 0
	v_cndmask_b32_e32 v0, 0, v0, vcc
	v_or_b32_e32 v0, v0, v139
	v_lshlrev_b32_e32 v56, 3, v158
	v_lshlrev_b32_e32 v74, 4, v158
	v_ashrrev_i32_e32 v1, 31, v0
	v_and_b32_e32 v70, 0x7f0, v74
	v_mov_b32_e32 v71, v69
	v_add_u32_e32 v52, 0x1000, v56
	v_bfe_u32 v64, v158, 4, 2
	v_lshlrev_b64 v[0:1], 11, v[0:1]
	s_waitcnt lgkmcnt(0)
	v_lshl_add_u64 v[48:49], s[10:11], 0, v[70:71]
	s_mov_b64 s[6:7], 0x1b00000
	v_and_b32_e32 v52, 0x3c00, v52
	v_lshl_add_u64 v[0:1], s[8:9], 0, v[0:1]
	v_lshlrev_b32_e32 v68, 4, v64
	v_lshl_add_u64 v[48:49], v[48:49], 0, s[6:7]
	v_and_b32_e32 v50, 0x3800, v74
	v_mov_b32_e32 v51, v69
	v_lshlrev_b32_e32 v52, 1, v52
	v_mov_b32_e32 v53, v69
	v_add_u32_e32 v54, 0x3000, v56
	v_lshl_add_u64 v[66:67], v[0:1], 0, v[68:69]
	v_lshl_add_u64 v[50:51], v[48:49], 0, v[50:51]
	v_lshl_add_u64 v[52:53], v[48:49], 0, v[52:53]
	s_movk_i32 s3, 0x4000
	v_and_b32_e32 v54, 0x7c00, v54
	global_load_dwordx4 v[0:3], v[66:67], off
	global_load_dwordx4 v[8:11], v[66:67], off offset:64
	global_load_dwordx4 v[4:7], v[66:67], off offset:128
	global_load_dwordx4 v[16:19], v[66:67], off offset:192
	global_load_dwordx4 v[12:15], v[66:67], off offset:256
	global_load_dwordx4 v[24:27], v[66:67], off offset:320
	global_load_dwordx4 v[20:23], v[66:67], off offset:384
	global_load_dwordx4 v[32:35], v[66:67], off offset:448
	global_load_dwordx4 v[28:31], v[66:67], off offset:512
	global_load_dwordx4 v[40:43], v[66:67], off offset:576
	global_load_dwordx4 v[36:39], v[66:67], off offset:640
	global_load_dwordx4 v[44:47], v[66:67], off offset:704
	global_load_dwordx4 v[76:79], v[50:51], off
	global_load_dwordx4 v[80:83], v[52:53], off
	v_add_co_u32_e64 v52, s[6:7], s3, v50
	v_lshlrev_b32_e32 v54, 1, v54
	v_mov_b32_e32 v55, v69
	v_addc_co_u32_e64 v53, s[6:7], 0, v51, s[6:7]
	v_lshl_add_u64 v[54:55], v[48:49], 0, v[54:55]
	global_load_dwordx4 v[84:87], v[52:53], off
	global_load_dwordx4 v[88:91], v[54:55], off
	s_mov_b32 s3, 0x8000
	v_add_u32_e32 v54, 0x5000, v56
	v_add_co_u32_e64 v52, s[6:7], s3, v50
	v_and_b32_e32 v54, 0x7c00, v54
	s_nop 0
	v_addc_co_u32_e64 v53, s[6:7], 0, v51, s[6:7]
	v_lshlrev_b32_e32 v54, 1, v54
	v_mov_b32_e32 v55, v69
	v_lshl_add_u64 v[54:55], v[48:49], 0, v[54:55]
	global_load_dwordx4 v[92:95], v[52:53], off
	global_load_dwordx4 v[96:99], v[54:55], off
	s_mov_b32 s3, 0xc000
	v_add_co_u32_e64 v50, s[6:7], s3, v50
	v_add_u32_e32 v65, 0, v70
	s_nop 0
	v_addc_co_u32_e64 v51, s[6:7], 0, v51, s[6:7]
	global_load_dwordx4 v[100:103], v[50:51], off
	v_add_u32_e32 v50, 0x7000, v56
	v_and_b32_e32 v50, 0xfc00, v50
	v_lshlrev_b32_e32 v50, 1, v50
	v_mov_b32_e32 v51, v69
	v_lshl_add_u64 v[108:109], v[48:49], 0, v[50:51]
	global_load_dwordx4 v[104:107], v[108:109], off
	global_load_dwordx4 v[52:55], v[66:67], off offset:768
	global_load_dwordx4 v[60:63], v[66:67], off offset:832
	global_load_dwordx4 v[56:59], v[66:67], off offset:896
	global_load_dwordx4 v[48:51], v[66:67], off offset:960
	v_add_u32_e32 v67, 0x200, v158
	v_lshrrev_b32_e32 v72, 7, v158
	s_movk_i32 s6, 0x810
	v_lshrrev_b32_e32 v67, 7, v67
	v_mad_u32_u24 v66, v72, s6, v65
	v_mad_u32_u24 v67, v67, s6, v65
	s_load_dword s3, s[0:1], 0x78
	s_mov_b32 s16, 0
	s_waitcnt vmcnt(11)
	ds_write_b128 v66, v[76:79]
	s_waitcnt vmcnt(10)
	ds_write_b128 v67, v[80:83]
	s_waitcnt vmcnt(9)
	ds_write_b128 v66, v[84:87] offset:16512
	v_add_u32_e32 v67, 0x600, v158
	v_lshrrev_b32_e32 v67, 7, v67
	v_mad_u32_u24 v67, v67, s6, v65
	s_waitcnt vmcnt(8)
	ds_write_b128 v67, v[88:91]
	s_waitcnt vmcnt(7)
	ds_write_b128 v66, v[92:95] offset:33024
	v_add_u32_e32 v67, 0xa00, v158
	v_lshrrev_b32_e32 v67, 7, v67
	v_mad_u32_u24 v67, v67, s6, v65
	s_waitcnt vmcnt(6)
	ds_write_b128 v67, v[96:99]
	s_waitcnt vmcnt(5)
	ds_write_b128 v66, v[100:103] offset:49536
	v_add_u32_e32 v66, 0xe00, v158
	v_lshrrev_b32_e32 v66, 7, v66
	v_mad_u32_u24 v65, v66, s6, v65
	s_waitcnt vmcnt(4)
	ds_write_b128 v65, v[104:107]
	s_waitcnt lgkmcnt(0)
	s_barrier
	s_and_saveexec_b64 s[6:7], vcc
	s_cbranch_execz .LBB0_179
	v_mul_u32_u24_e32 v70, 0x810, v139
	v_lshlrev_b32_e32 v64, 3, v64
	v_lshl_add_u64 v[66:67], s[10:11], 0, v[68:69]
	v_add3_u32 v75, 0, v70, v68
	v_lshlrev_b32_e32 v68, 4, v140
	v_lshlrev_b32_e32 v64, 1, v64
	v_mov_b32_e32 v65, v69
	s_mov_b64 s[14:15], 0x500000
	v_lshl_add_u32 v68, s100, 7, v68
	s_lshl_b32 s17, s3, 3
	s_cmp_eq_u32 s3, 0x100
	s_cselect_b32 s17, 0x400, s17
	v_lshl_add_u64 v[64:65], s[8:9], 0, v[64:65]
	v_lshl_add_u64 v[66:67], v[66:67], 0, s[14:15]
	v_or_b32_e32 v68, v68, v139
	s_lshl_b32 s18, s3, 7
	s_cmp_eq_u32 s3, 0x100
	s_cselect_b32 s18, 0x4000, s18
	s_mov_b64 s[14:15], 0
	s_movk_i32 s19, 0x7ff
	s_branch .LBB0_177

.LBB0_349:
	s_lshr_b32 s34, s16, 6
	s_and_b64 s[18:19], exec, s[38:39]
	s_cselect_b32 s7, 0, 0x4000000
	s_add_u32 s7, s24, s7
	s_addc_u32 s9, s25, 0
	s_ashr_i32 s11, s10, 31
	s_lshl_b64 s[18:19], s[10:11], 20
	s_add_u32 s43, s7, s18
	s_addc_u32 s63, s9, s19
	s_and_b64 s[44:45], exec, s[38:39]
	s_cselect_b32 s7, s59, 0x6000000
	s_add_u32 s7, s24, s7
	s_addc_u32 s9, s25, 0
	s_add_u32 s64, s7, s18
	s_addc_u32 s65, s9, s19
	s_lshl_b64 s[14:15], s[14:15], 1
	s_add_u32 s46, s51, s14
	s_addc_u32 s47, s52, s15
	s_lshl_b32 s7, s10, 7
	s_lshl_b32 s9, s17, 6
	s_or_b32 s10, s7, s9
	s_ashr_i32 s11, s10, 31
	s_lshl_b64 s[10:11], s[10:11], 10
	s_ashr_i32 s31, s30, 31
	s_add_u32 s48, s33, s10
	s_addc_u32 s49, s50, s11
	s_lshr_b32 s18, s16, 7
	s_lshl_b64 s[10:11], s[30:31], 7
	s_bfe_u32 s31, s16, 0x20006
	s_and_b32 s66, s18, 0x1fffffe
	s_lshl_b32 s7, s12, 13
	s_lshl_b32 s9, s12, 14
	s_add_u32 s14, s43, s9
	s_addc_u32 s15, s63, 0
	v_lshl_add_u64 v[0:1], s[14:15], 0, v[120:121]
	s_add_u32 s16, s64, s9
	v_add_co_u32_e32 v0, vcc, s60, v0
	s_addc_u32 s17, s65, 0
	s_nop 0
	v_addc_co_u32_e32 v1, vcc, 0, v1, vcc
	v_lshl_add_u64 v[2:3], s[16:17], 0, v[120:121]
	v_add_co_u32_e32 v2, vcc, s60, v2
	global_load_dwordx4 v[56:59], v120, s[14:15]
	global_load_dwordx4 v[60:63], v120, s[16:17]
	v_addc_co_u32_e32 v3, vcc, 0, v3, vcc
	global_load_dwordx4 v[64:67], v[0:1], off
	global_load_dwordx4 v[68:71], v[2:3], off
	s_add_u32 s14, s46, s7
	s_addc_u32 s15, s47, 0
	global_load_dwordx4 v[72:75], v120, s[14:15]
	s_lshl_b32 s7, s12, 10
	s_add_u32 s12, s48, s7
	s_addc_u32 s13, s49, 0
	global_load_dwordx4 v[76:79], v142, s[12:13]
	global_load_dwordx4 v[0:3], v[126:127], off
	global_load_dwordx4 v[4:7], v[126:127], off offset:16
	global_load_dwordx4 v[8:11], v[128:129], off
	global_load_dwordx4 v[12:15], v[128:129], off offset:16
	global_load_dwordx4 v[16:19], v[130:131], off
	global_load_dwordx4 v[20:23], v[130:131], off offset:16
	global_load_dwordx4 v[24:27], v[132:133], off
	global_load_dwordx4 v[28:31], v[132:133], off offset:16
	s_waitcnt vmcnt(34)
	v_add_u32_e32 v32, 0, v154
	v_or_b32_e32 v144, s10, v122
	v_mov_b32_e32 v33, v121
	s_waitcnt vmcnt(20)
	v_add_u32_e32 v82, 0x1e400, v32
	v_and_b32_e32 v32, 0xf87, v144
	v_cmp_ne_u64_e32 vcc, 0, v[32:33]
	s_lshl_b32 s7, s8, 13
	s_lshl_b32 s9, s8, 14
	v_cndmask_b32_e64 v32, 0, 1, vcc
	s_add_u32 s10, s43, s9
	v_mov_b32_e32 v145, s11
	v_mov_b32_e32 v34, s11
	v_sub_co_u32_e32 v80, vcc, v144, v32
	s_addc_u32 s11, s63, 0
	s_nop 0
	v_subbrev_co_u32_e32 v81, vcc, 0, v34, vcc
	v_lshl_add_u64 v[36:37], s[10:11], 0, v[120:121]
	global_load_dwordx4 v[32:35], v120, s[10:11]
	s_add_u32 s10, s64, s9
	v_add_co_u32_e32 v36, vcc, s60, v36
	s_addc_u32 s11, s65, 0
	s_nop 0
	v_addc_co_u32_e32 v37, vcc, 0, v37, vcc
	v_lshl_add_u64 v[38:39], s[10:11], 0, v[120:121]
	s_add_u32 s12, s46, s7
	v_add_co_u32_e32 v40, vcc, s60, v38
	s_addc_u32 s13, s47, 0
	s_lshl_b32 s7, s8, 10
	v_addc_co_u32_e32 v41, vcc, 0, v39, vcc
	s_add_u32 s8, s48, s7
	global_load_dwordx4 v[36:39], v[36:37], off
	s_nop 0
	global_load_dwordx4 v[44:47], v[40:41], off
	s_nop 0
	global_load_dwordx4 v[40:43], v120, s[10:11]
	global_load_dwordx4 v[48:51], v120, s[12:13]
	s_addc_u32 s9, s49, 0
	s_lshl_b32 s7, s6, 13
	s_lshl_b32 s10, s6, 14
	global_load_dwordx4 v[52:55], v142, s[8:9]
	s_add_u32 s8, s43, s10
	s_addc_u32 s9, s63, 0
	s_add_u32 s10, s64, s10
	s_addc_u32 s11, s65, 0
	s_mul_i32 s67, s31, 0x1100
	v_add_u32_e32 v170, s67, v155
	v_lshl_or_b32 v173, s66, 4, v123
	v_mul_lo_u32 v174, v173, s3
	s_mov_b32 s44, 0
	s_mov_b32 s45, s44
	v_mov_b32_e32 v143, v121
	v_lshl_add_u32 v178, s34, 5, v160
	v_add_u32_e32 v181, 0xf000, v178
	v_add_u32_e32 v183, s67, v157
	s_waitcnt vmcnt(19)
	ds_write_b128 v168, v[56:59]
	s_waitcnt vmcnt(17)
	ds_write_b128 v168, v[64:67] offset:8704
	ds_write_b128 v168, v[60:63] offset:17408
	s_waitcnt vmcnt(16)
	ds_write_b128 v168, v[68:71] offset:26112
	s_waitcnt vmcnt(15)
	ds_write_b128 v169, v[72:75] offset:34816
	s_waitcnt vmcnt(14)
	ds_write_b128 v82, v[76:79]
	v_lshlrev_b64 v[56:57], 11, v[80:81]
	v_lshlrev_b64 v[64:65], 11, v[144:145]
	v_lshl_add_u64 v[72:73], s[8:9], 0, v[120:121]
	v_lshl_add_u64 v[56:57], v[134:135], 0, v[56:57]
	v_lshl_add_u64 v[66:67], v[134:135], 0, v[64:65]
	v_lshl_add_u64 v[68:69], v[136:137], 0, v[64:65]
	v_add_co_u32_e32 v80, vcc, s60, v72
	global_load_dwordx4 v[56:59], v[56:57], off
	s_nop 0
	global_load_dwordx4 v[60:63], v[66:67], off
	s_nop 0
	global_load_dwordx4 v[64:67], v[66:67], off offset:2048
	s_nop 0
	global_load_dwordx4 v[68:71], v[68:69], off
	v_addc_co_u32_e32 v81, vcc, 0, v73, vcc
	global_load_dwordx4 v[72:75], v120, s[8:9]
	global_load_dwordx4 v[76:79], v120, s[10:11]
	s_add_u32 s8, s46, s7
	v_lshl_add_u64 v[82:83], s[10:11], 0, v[120:121]
	s_addc_u32 s9, s47, 0
	s_lshl_b32 s6, s6, 10
	v_add_co_u32_e32 v84, vcc, s60, v82
	s_add_u32 s6, s48, s6
	s_nop 0
	v_addc_co_u32_e32 v85, vcc, 0, v83, vcc
	s_addc_u32 s7, s49, 0
	global_load_dwordx4 v[80:83], v[80:81], off
	s_nop 0
	global_load_dwordx4 v[84:87], v[84:85], off
	s_lshl_b32 s12, s18, 4
	global_load_dwordx4 v[88:91], v120, s[8:9]
	global_load_dwordx4 v[92:95], v142, s[6:7]
	s_waitcnt lgkmcnt(0)
	s_barrier
	ds_read_b128 v[96:99], v170 offset:17408
	s_mul_i32 s6, s66, 0x1100
	v_add_u32_e32 v171, s6, v155
	ds_read_b128 v[100:103], v171
	s_or_b32 s68, s12, 16
	ds_read_b128 v[104:107], v170 offset:17472
	ds_read_b128 v[108:111], v171 offset:64
	s_mul_i32 s6, s68, 0x110
	s_waitcnt lgkmcnt(2)
	v_mfma_f32_16x16x32_bf16 v[100:103], v[96:99], v[100:103], 0
	v_add_u32_e32 v172, s6, v155
	ds_read_b128 v[112:115], v172
	ds_read_b128 v[116:119], v172 offset:64
	v_or_b32_e32 v179, s68, v123
	s_waitcnt lgkmcnt(2)
	v_mfma_f32_16x16x32_bf16 v[100:103], v[104:107], v[108:111], v[100:103]
	ds_read_b128 v[108:111], v170 offset:17536
	v_mov_b32_e32 v184, v165
	v_mov_b64_e32 v[152:153], v[140:141]
	s_waitcnt lgkmcnt(2)
	v_mfma_f32_16x16x32_bf16 v[96:99], v[96:99], v[112:115], 0
	s_waitcnt lgkmcnt(1)
	v_mfma_f32_16x16x32_bf16 v[96:99], v[104:107], v[116:119], v[96:99]
	ds_read_b128 v[104:107], v171 offset:128
	ds_read_b128 v[112:115], v170 offset:17600
	ds_read_b128 v[116:119], v171 offset:192
	s_waitcnt lgkmcnt(2)
	v_mfma_f32_16x16x32_bf16 v[100:103], v[108:111], v[104:107], v[100:103]
	ds_read_b128 v[104:107], v172 offset:128
	ds_read_b128 v[146:149], v172 offset:192
	s_waitcnt lgkmcnt(1)
	v_mfma_f32_16x16x32_bf16 v[96:99], v[108:111], v[104:107], v[96:99]
	v_lshl_or_b32 v104, s31, 4, v124
	v_or_b32_e32 v107, 2, v104
	v_or_b32_e32 v108, 3, v104
	v_mfma_f32_16x16x32_bf16 v[100:103], v[112:115], v[116:119], v[100:103]
	v_cmp_gt_u32_e32 vcc, v104, v173
	v_cmp_ge_u32_e64 s[6:7], v104, v173
	v_cmp_gt_u32_e64 s[8:9], v107, v173
	v_cmp_gt_u32_e64 s[10:11], v108, v173
	v_lshlrev_b32_e32 v105, 1, v104
	s_xor_b64 vcc, s[38:39], vcc
	s_xor_b64 s[6:7], s[38:39], s[6:7]
	s_xor_b64 s[8:9], s[38:39], s[8:9]
	s_xor_b64 s[10:11], s[38:39], s[10:11]
	v_add_u32_e32 v106, s57, v105
	v_cndmask_b32_e32 v100, 0, v100, vcc
	v_cndmask_b32_e64 v101, 0, v101, s[6:7]
	v_cndmask_b32_e64 v102, 0, v102, s[8:9]
	v_cndmask_b32_e64 v103, 0, v103, s[10:11]
	s_waitcnt lgkmcnt(0)
	v_mfma_f32_16x16x32_bf16 v[96:99], v[112:115], v[146:149], v[96:99]
	v_cvt_pk_bf16_f32 v100, v100, v101
	v_cvt_pk_bf16_f32 v101, v102, v103
	v_add_u32_e32 v175, v106, v174
	ds_write_b64 v175, v[100:101]
	v_or_b32_e32 v100, s12, v164
	v_cmp_gt_u32_e64 s[12:13], v104, v100
	v_cmp_ge_u32_e64 s[14:15], v104, v100
	v_cmp_gt_u32_e64 s[16:17], v107, v100
	v_cmp_gt_u32_e64 s[18:19], v108, v100
	s_xor_b64 s[12:13], s[38:39], s[12:13]
	s_xor_b64 s[14:15], s[38:39], s[14:15]
	s_xor_b64 s[16:17], s[38:39], s[16:17]
	s_xor_b64 s[18:19], s[38:39], s[18:19]
	v_cndmask_b32_e64 v96, 0, v96, s[12:13]
	v_cndmask_b32_e64 v97, 0, v97, s[14:15]
	v_cndmask_b32_e64 v98, 0, v98, s[16:17]
	v_cndmask_b32_e64 v99, 0, v99, s[18:19]
	v_mul_lo_u32 v176, v100, s3
	v_cvt_pk_bf16_f32 v96, v96, v97
	v_cvt_pk_bf16_f32 v97, v98, v99
	v_add_u32_e32 v177, v106, v176
	ds_write_b64 v177, v[96:97]
	v_mov_b64_e32 v[96:97], s[44:45]
	global_store_dwordx2 v[138:139], v[96:97], off
	global_store_dwordx2 v[138:139], v[96:97], off
	global_store_dwordx2 v[138:139], v[96:97], off
	global_store_dwordx2 v[138:139], v[96:97], off
	global_store_dwordx2 v[138:139], v[96:97], off
	s_lshl_b32 s31, s31, 5
	global_store_dwordx2 v[138:139], v[96:97], off
	v_lshl_or_b32 v96, s34, 4, v124
	s_add_u32 s20, s20, s31
	s_waitcnt lgkmcnt(0)
	v_lshl_add_u64 v[148:149], s[48:49], 0, v[142:143]
	v_lshlrev_b32_e32 v143, 2, v96
	v_lshlrev_b32_e32 v98, 1, v96
	s_addc_u32 s21, s21, 0
	v_lshlrev_b32_e32 v96, 1, v124
	v_mov_b32_e32 v97, v121
	v_lshl_add_u64 v[150:151], s[20:21], 0, v[96:97]
	v_mov_b32_e32 v100, 0
	v_mov_b32_e32 v96, 1.0
	v_lshl_add_u64 v[146:147], s[46:47], 0, v[120:121]
	s_mul_i32 s45, s66, 0x900
	s_mul_i32 s46, s68, 0x90
	v_add_u32_e32 v180, s58, v105
	s_mov_b32 s47, 62
	v_add_u32_e32 v182, v163, v98
	v_mov_b32_e32 v97, v96
	v_mov_b32_e32 v98, v96
	v_mov_b32_e32 v99, v96
	v_mov_b32_e32 v101, v100
	v_mov_b32_e32 v102, v100
	v_mov_b32_e32 v103, v100
	v_mov_b32_e32 v104, v100
	v_mov_b32_e32 v105, v100
	v_mov_b32_e32 v106, v100
	v_mov_b32_e32 v107, v100
	v_mov_b32_e32 v108, v100
	v_mov_b32_e32 v109, v100
	v_mov_b32_e32 v110, v100
	v_mov_b32_e32 v111, v100
	v_mov_b32_e32 v112, v100
	v_mov_b32_e32 v113, v100
	v_mov_b32_e32 v114, v100
	v_mov_b32_e32 v115, v100
	v_add_u32_e32 v206, s31, v161
	v_add_u32_e32 v207, s31, v162
	v_add_u32_e32 v208, s45, v156
	v_add_u32_e32 v209, s46, v156
	v_add_u32_e32 v210, s45, v159
	v_add_u32_e32 v211, s46, v159
	v_add_u32_e32 v212, v180, v174
	v_add_u32_e32 v213, v180, v176
	v_readfirstlane_b32 s69, v158
	s_lshr_b32 s69, s69, 6
.LBB0_350:
	s_add_i32 s34, s47, 1
	s_and_b64 s[20:21], exec, s[38:39]
	s_cselect_b32 s48, s44, s34
	s_waitcnt vmcnt(20)
	ds_write_b128 v168, v[32:35] offset:44032
	s_waitcnt vmcnt(19)
	ds_write_b128 v168, v[36:39] offset:52736
	s_waitcnt vmcnt(18)
	ds_write_b128 v168, v[40:43] offset:61440
	s_waitcnt vmcnt(17)
	ds_write_b128 v166, v[44:47] offset:8704
	s_waitcnt vmcnt(16)
	ds_write_b128 v167, v[48:51]
	v_add_u32_e32 v32, s61, v154
	s_min_u32 s49, s44, 60
	s_waitcnt vmcnt(15)
	s_cmp_lg_u32 s69, 0
	s_cbranch_scc1 .Lev_skip_a
	ds_write_b128 v32, v[52:55]
.Lev_skip_a:
	v_add_u32_e32 v32, 0, v125
	s_add_i32 s34, s49, 3
	v_add_u32_e32 v186, 0x1ec00, v32
	v_add_u32_e32 v187, 0x20c00, v32
	v_add_u32_e32 v188, 0x22c00, v32
	v_add_u32_e32 v189, 0x24c00, v32
	v_sub_u32_e64 v32, 60, s44 clamp
	s_and_b64 s[20:21], exec, s[38:39]
	v_readfirstlane_b32 s20, v32
	s_cselect_b32 s66, s34, s20
	s_lshl_b32 s34, s66, 13
	s_lshl_b32 s67, s66, 14
	s_add_u32 s20, s43, s67
	s_addc_u32 s21, s63, 0
	v_lshl_add_u64 v[36:37], s[20:21], 0, v[120:121]
	global_load_dwordx4 v[32:35], v120, s[20:21]
	v_add_co_u32_e64 v36, s[20:21], s60, v36
	v_lshl_add_u64 v[48:49], v[146:147], 0, s[34:35]
	s_nop 0
	v_addc_co_u32_e64 v37, s[20:21], 0, v37, s[20:21]
	s_add_u32 s20, s64, s67
	s_addc_u32 s21, s65, 0
	v_lshl_add_u64 v[44:45], s[20:21], 0, v[120:121]
	global_load_dwordx4 v[36:39], v[36:37], off
	s_lshl_b32 s34, s66, 10
	global_load_dwordx4 v[40:43], v120, s[20:21]
	v_add_co_u32_e64 v44, s[20:21], s60, v44
	v_lshl_add_u64 v[52:53], v[148:149], 0, s[34:35]
	s_nop 0
	v_addc_co_u32_e64 v45, s[20:21], 0, v45, s[20:21]
	s_lshl_b32 s20, s49, 1
	s_add_i32 s34, s20, 4
	s_waitcnt vmcnt(15)
	ds_write_b128 v188, v[64:67]
	v_lshl_add_u64 v[64:65], v[144:145], 0, s[34:35]
	s_add_i32 s34, 0, 0x1e400
	ds_write_b128 v186, v[56:59]
	ds_write_b128 v187, v[60:63]
	s_waitcnt vmcnt(14)
	ds_write_b128 v189, v[68:71]
	v_add_u32_e32 v116, s34, v143
	ds_read_b128 v[190:193], v116
	v_and_b32_e32 v66, 0xfff, v64
	v_cmp_ne_u32_e64 s[20:21], 0, v66
	v_add_u32_e32 v185, 0, v143
	v_add_u32_e32 v116, 0x1e600, v185
	s_waitcnt lgkmcnt(0)
	v_pk_mul_f32 v[192:193], v[98:99], v[192:193]
	v_pk_mul_f32 v[190:191], v[96:97], v[190:191]
	v_pk_mul_f32 v[98:99], v[102:103], v[192:193]
	v_pk_mul_f32 v[96:97], v[100:101], v[190:191]
	v_cndmask_b32_e64 v56, 0, 1, s[20:21]
	v_cvt_pk_bf16_f32 v100, v96, v97
	v_cvt_pk_bf16_f32 v101, v98, v99
	v_sub_co_u32_e64 v56, s[20:21], v64, v56
	ds_read_b128 v[116:119], v116
	ds_write_b64 v182, v[100:101]
	v_pk_mul_f32 v[100:101], v[104:105], v[190:191]
	v_pk_mul_f32 v[102:103], v[106:107], v[192:193]
	v_subbrev_co_u32_e64 v57, s[20:21], 0, v65, s[20:21]
	v_cvt_pk_bf16_f32 v104, v100, v101
	v_cvt_pk_bf16_f32 v105, v102, v103
	v_cmp_ne_u32_e64 s[20:21], s62, v66
	ds_write_b64 v182, v[104:105] offset:4352
	v_pk_mul_f32 v[104:105], v[108:109], v[190:191]
	v_pk_mul_f32 v[106:107], v[110:111], v[192:193]
	v_cndmask_b32_e64 v66, 0, 1, s[20:21]
	v_mov_b32_e32 v67, s35
	v_cvt_pk_bf16_f32 v108, v104, v105
	v_cvt_pk_bf16_f32 v109, v106, v107
	v_lshlrev_b64 v[68:69], 11, v[64:65]
	v_lshl_add_u64 v[64:65], v[64:65], 0, v[66:67]
	ds_write_b64 v182, v[108:109] offset:8704
	v_pk_mul_f32 v[108:109], v[112:113], v[190:191]
	v_pk_mul_f32 v[110:111], v[114:115], v[192:193]
	v_lshlrev_b64 v[56:57], 11, v[56:57]
	v_lshlrev_b64 v[64:65], 11, v[64:65]
	v_cvt_pk_bf16_f32 v112, v108, v109
	v_cvt_pk_bf16_f32 v113, v110, v111
	v_lshl_add_u64 v[56:57], v[134:135], 0, v[56:57]
	v_lshl_add_u64 v[60:61], v[134:135], 0, v[68:69]
	v_lshl_add_u64 v[64:65], v[134:135], 0, v[64:65]
	v_lshl_add_u64 v[68:69], v[136:137], 0, v[68:69]
	ds_write_b64 v182, v[112:113] offset:13056
	global_load_dwordx4 v[44:47], v[44:45], off
	v_add_u32_e32 v198, s31, v161
	global_load_dwordx4 v[48:51], v[48:49], off
	v_add_u32_e32 v199, s45, v156
	global_load_dwordx4 v[52:55], v[52:53], off
	v_add_u32_e32 v202, s46, v156
	global_load_dwordx4 v[56:59], v[56:57], off
	s_lshl_b32 s48, s48, 6
	global_load_dwordx4 v[60:63], v[60:61], off
	s_nop 0
	global_load_dwordx4 v[64:67], v[64:65], off
	s_nop 0
	global_load_dwordx4 v[68:71], v[68:69], off
	s_waitcnt lgkmcnt(0)
	s_barrier
	ds_read_b128 v[198:201], v186
	ds_read_b128 v[202:205], v187
	ds_read_b128 v[214:217], v188
	ds_read_b128 v[242:245], v189
	ds_read_b128 v[218:221], v170 offset:61440
	ds_read_b128 v[222:225], v171 offset:44032
	ds_read_b128 v[226:229], v172 offset:44032
	ds_read_b64_tr_b16 v[230:231], v178 offset:17408
	ds_read_b64_tr_b16 v[232:233], v178 offset:18496
	ds_read_b64_tr_b16 v[234:235], v161 offset:34816
	ds_read_b64_tr_b16 v[236:237], v161 offset:35392
	ds_read_b64_tr_b16 v[238:239], v161 offset:34848
	ds_read_b64_tr_b16 v[240:241], v161 offset:35424
	v_and_b32_e32 v250, 0xfff, v184
	v_cmp_ne_u32_e64 s[20:21], 0, v250
	v_add_u32_e32 v184, 4, v184
	s_waitcnt lgkmcnt(9)
	v_cndmask_b32_e64 v198, 0, v198, s[20:21]
	v_cndmask_b32_e64 v199, 0, v199, s[20:21]
	v_cndmask_b32_e64 v200, 0, v200, s[20:21]
	v_cndmask_b32_e64 v201, 0, v201, s[20:21]
	v_cmp_ne_u32_e64 s[20:21], s62, v250
	v_lshlrev_b32_e32 v246, 16, v202
	v_and_b32_e32 v247, 0xffff0000, v202
	v_cndmask_b32_e64 v214, 0, v214, s[20:21]
	v_cndmask_b32_e64 v215, 0, v215, s[20:21]
	v_cndmask_b32_e64 v216, 0, v216, s[20:21]
	v_cndmask_b32_e64 v217, 0, v217, s[20:21]
	v_pk_mul_f32 v[246:247], v[8:9], v[246:247]
	v_lshlrev_b32_e32 v248, 16, v198
	v_and_b32_e32 v249, 0xffff0000, v198
	v_pk_fma_f32 v[246:247], v[0:1], v[248:249], v[246:247]
	v_lshlrev_b32_e32 v248, 16, v214
	v_and_b32_e32 v249, 0xffff0000, v214
	v_pk_fma_f32 v[246:247], v[16:17], v[248:249], v[246:247]
	v_pk_add_f32 v[246:247], v[24:25], v[246:247]
	v_lshlrev_b32_e32 v248, 16, v242
	v_and_b32_e32 v249, 0xffff0000, v242
	v_pk_mul_f32 v[246:247], v[246:247], v[248:249]
	v_cvt_pk_bf16_f32 v198, v246, v247
	v_lshlrev_b32_e32 v246, 16, v203
	v_and_b32_e32 v247, 0xffff0000, v203
	v_pk_mul_f32 v[246:247], v[10:11], v[246:247]
	v_lshlrev_b32_e32 v248, 16, v199
	v_and_b32_e32 v249, 0xffff0000, v199
	v_pk_fma_f32 v[246:247], v[2:3], v[248:249], v[246:247]
	v_lshlrev_b32_e32 v248, 16, v215
	v_and_b32_e32 v249, 0xffff0000, v215
	v_pk_fma_f32 v[246:247], v[18:19], v[248:249], v[246:247]
	v_pk_add_f32 v[246:247], v[26:27], v[246:247]
	v_lshlrev_b32_e32 v248, 16, v243
	v_and_b32_e32 v249, 0xffff0000, v243
	v_pk_mul_f32 v[246:247], v[246:247], v[248:249]
	v_cvt_pk_bf16_f32 v199, v246, v247
	v_lshlrev_b32_e32 v246, 16, v204
	v_and_b32_e32 v247, 0xffff0000, v204
	v_pk_mul_f32 v[246:247], v[12:13], v[246:247]
	v_lshlrev_b32_e32 v248, 16, v200
	v_and_b32_e32 v249, 0xffff0000, v200
	v_pk_fma_f32 v[246:247], v[4:5], v[248:249], v[246:247]
	v_lshlrev_b32_e32 v248, 16, v216
	v_and_b32_e32 v249, 0xffff0000, v216
	v_pk_fma_f32 v[246:247], v[20:21], v[248:249], v[246:247]
	v_pk_add_f32 v[246:247], v[28:29], v[246:247]
	v_lshlrev_b32_e32 v248, 16, v244
	v_and_b32_e32 v249, 0xffff0000, v244
	v_pk_mul_f32 v[246:247], v[246:247], v[248:249]
	v_cvt_pk_bf16_f32 v200, v246, v247
	v_lshlrev_b32_e32 v246, 16, v205
	v_and_b32_e32 v247, 0xffff0000, v205
	v_pk_mul_f32 v[246:247], v[14:15], v[246:247]
	v_lshlrev_b32_e32 v248, 16, v201
	v_and_b32_e32 v249, 0xffff0000, v201
	v_pk_fma_f32 v[246:247], v[6:7], v[248:249], v[246:247]
	v_lshlrev_b32_e32 v248, 16, v217
	v_and_b32_e32 v249, 0xffff0000, v217
	v_pk_fma_f32 v[246:247], v[22:23], v[248:249], v[246:247]
	v_pk_add_f32 v[246:247], v[30:31], v[246:247]
	v_lshlrev_b32_e32 v248, 16, v245
	v_and_b32_e32 v249, 0xffff0000, v245
	v_pk_mul_f32 v[246:247], v[246:247], v[248:249]
	v_cvt_pk_bf16_f32 v201, v246, v247
	global_store_dwordx4 v[152:153], v[198:201], off
	ds_read_b128 v[242:245], v170 offset:61504
	ds_read_b128 v[246:249], v171 offset:44096
	ds_read_b128 v[250:253], v172 offset:44096
	s_waitcnt lgkmcnt(9)
	v_mfma_f32_16x16x32_bf16 v[190:193], v[218:221], v[222:225], 0
	v_mfma_f32_16x16x32_bf16 v[194:197], v[218:221], v[226:229], 0
	ds_read_b64_tr_b16 v[218:219], v178 offset:17408
	ds_read_b64_tr_b16 v[220:221], v178 offset:18496
	ds_read_b64_tr_b16 v[222:223], v161 offset:34880
	ds_read_b64_tr_b16 v[224:225], v161 offset:35456
	ds_read_b64_tr_b16 v[226:227], v161 offset:34912
	ds_read_b64_tr_b16 v[228:229], v161 offset:35488
	s_waitcnt lgkmcnt(9)
	v_mfma_f32_16x16x32_bf16 v[96:99], v[230:233], v[234:237], v[96:99]
	v_mfma_f32_16x16x32_bf16 v[100:103], v[230:233], v[238:241], v[100:103]
	ds_read_b128 v[230:233], v170 offset:61568
	ds_read_b128 v[234:237], v171 offset:44160
	ds_read_b128 v[238:241], v172 offset:44160
	s_waitcnt lgkmcnt(9)
	v_mfma_f32_16x16x32_bf16 v[190:193], v[242:245], v[246:249], v[190:193]
	v_mfma_f32_16x16x32_bf16 v[194:197], v[242:245], v[250:253], v[194:197]
	ds_read_b64_tr_b16 v[242:243], v206 offset:34816
	ds_read_b64_tr_b16 v[244:245], v206 offset:35392
	ds_read_b128 v[246:249], v208
	ds_read_b128 v[250:253], v209
	s_waitcnt lgkmcnt(7)
	v_mfma_f32_16x16x32_bf16 v[104:107], v[218:221], v[222:225], v[104:107]
	v_mfma_f32_16x16x32_bf16 v[214:217], v[218:221], v[226:229], v[108:111]
	ds_read_b128 v[218:221], v170 offset:61632
	ds_read_b128 v[222:225], v171 offset:44224
	ds_read_b128 v[226:229], v172 offset:44224
	s_waitcnt lgkmcnt(7)
	v_mfma_f32_16x16x32_bf16 v[190:193], v[230:233], v[234:237], v[190:193]
	v_mfma_f32_16x16x32_bf16 v[194:197], v[230:233], v[238:241], v[194:197]
	ds_read_b64_tr_b16 v[230:231], v206 offset:39424
	ds_read_b64_tr_b16 v[232:233], v206 offset:40000
	ds_read_b128 v[234:237], v208 offset:64
	ds_read_b128 v[238:241], v209 offset:64
	s_waitcnt lgkmcnt(7)
	v_mfma_f32_16x16x32_bf16 v[198:201], v[242:245], v[246:249], 0
	v_mfma_f32_16x16x32_bf16 v[202:205], v[242:245], v[250:253], 0
	ds_read_b128 v[242:245], v183
	ds_read_b128 v[246:249], v171
	ds_read_b128 v[250:253], v172
	s_waitcnt lgkmcnt(7)
	v_mfma_f32_16x16x32_bf16 v[190:193], v[218:221], v[222:225], v[190:193]
	v_mfma_f32_16x16x32_bf16 v[194:197], v[218:221], v[226:229], v[194:197]
	ds_read_b128 v[218:221], v183 offset:64
	ds_read_b128 v[222:225], v171 offset:64
	ds_read_b128 v[226:229], v172 offset:64
	s_waitcnt lgkmcnt(6)
	v_mfma_f32_16x16x32_bf16 v[198:201], v[230:233], v[234:237], v[198:201]
	v_mfma_f32_16x16x32_bf16 v[202:205], v[230:233], v[238:241], v[202:205]
	ds_read_b128 v[230:233], v183 offset:128
	ds_read_b128 v[234:237], v171 offset:128
	ds_read_b128 v[238:241], v172 offset:128
	v_cndmask_b32_e32 v190, 0, v190, vcc
	v_cndmask_b32_e64 v191, 0, v191, s[6:7]
	v_cndmask_b32_e64 v192, 0, v192, s[8:9]
	v_cndmask_b32_e64 v193, 0, v193, s[10:11]
	v_cvt_pk_bf16_f32 v190, v190, v191
	v_cvt_pk_bf16_f32 v191, v192, v193
	v_cndmask_b32_e64 v194, 0, v194, s[12:13]
	v_cndmask_b32_e64 v195, 0, v195, s[14:15]
	v_cndmask_b32_e64 v196, 0, v196, s[16:17]
	v_cndmask_b32_e64 v197, 0, v197, s[18:19]
	v_cvt_pk_bf16_f32 v194, v194, v195
	v_cvt_pk_bf16_f32 v195, v196, v197
	ds_write_b64 v212, v[190:191]
	ds_write_b64 v213, v[194:195]
	s_waitcnt lgkmcnt(8)
	v_mfma_f32_16x16x32_bf16 v[198:201], v[242:245], v[246:249], v[198:201]
	v_mfma_f32_16x16x32_bf16 v[202:205], v[242:245], v[250:253], v[202:205]
	ds_read_b128 v[242:245], v183 offset:192
	ds_read_b128 v[246:249], v171 offset:192
	ds_read_b128 v[250:253], v172 offset:192
	s_waitcnt lgkmcnt(8)
	v_mfma_f32_16x16x32_bf16 v[198:201], v[218:221], v[222:225], v[198:201]
	v_mfma_f32_16x16x32_bf16 v[202:205], v[218:221], v[226:229], v[202:205]
	ds_read_b64_tr_b16 v[218:219], v178 offset:26112
	ds_read_b64_tr_b16 v[220:221], v178 offset:27200
	ds_read_b64_tr_b16 v[222:223], v161 offset:39424
	ds_read_b64_tr_b16 v[224:225], v161 offset:40000
	ds_read_b64_tr_b16 v[226:227], v161 offset:39456
	ds_read_b64_tr_b16 v[228:229], v161 offset:40032
	s_waitcnt lgkmcnt(11)
	v_mfma_f32_16x16x32_bf16 v[198:201], v[230:233], v[234:237], v[198:201]
	v_mfma_f32_16x16x32_bf16 v[202:205], v[230:233], v[238:241], v[202:205]
	ds_read_b64_tr_b16 v[230:231], v178 offset:26112
	ds_read_b64_tr_b16 v[232:233], v178 offset:27200
	ds_read_b64_tr_b16 v[234:235], v161 offset:39488
	ds_read_b64_tr_b16 v[236:237], v161 offset:40064
	ds_read_b64_tr_b16 v[238:239], v161 offset:39520
	ds_read_b64_tr_b16 v[240:241], v161 offset:40096
	s_waitcnt lgkmcnt(12)
	v_mfma_f32_16x16x32_bf16 v[198:201], v[242:245], v[246:249], v[198:201]
	v_mfma_f32_16x16x32_bf16 v[202:205], v[242:245], v[250:253], v[202:205]
	s_waitcnt lgkmcnt(6)
	v_mfma_f32_16x16x32_bf16 v[112:115], v[218:221], v[222:225], v[96:99]
	v_mfma_f32_16x16x32_bf16 v[108:111], v[218:221], v[226:229], v[100:103]
	s_nop 3
	v_cvt_pk_bf16_f32 v198, v198, v199
	v_cvt_pk_bf16_f32 v199, v200, v201
	v_add_u32_e32 v254, s48, v173
	v_mad_u64_u32 v[254:255], s[20:21], v254, s42, 0
	v_lshl_add_u64 v[254:255], v[254:255], 1, v[150:151]
	v_cvt_pk_bf16_f32 v202, v202, v203
	v_cvt_pk_bf16_f32 v203, v204, v205
	global_store_dwordx2 v[254:255], v[198:199], off
	v_add_u32_e32 v254, s48, v179
	v_mad_u64_u32 v[254:255], s[20:21], v254, s42, 0
	v_lshl_add_u64 v[254:255], v[254:255], 1, v[150:151]
	global_store_dwordx2 v[254:255], v[202:203], off
	s_waitcnt lgkmcnt(0)
	v_mfma_f32_16x16x32_bf16 v[104:107], v[230:233], v[234:237], v[104:107]
	v_mfma_f32_16x16x32_bf16 v[100:103], v[230:233], v[238:241], v[214:217]
	s_min_u32 s20, s44, 59
	s_waitcnt lgkmcnt(0)
	s_barrier
	s_waitcnt vmcnt(20)
	ds_write_b128 v168, v[72:75]
	s_waitcnt vmcnt(19)
	ds_write_b128 v168, v[80:83] offset:8704
	s_waitcnt vmcnt(18)
	ds_write_b128 v168, v[76:79] offset:17408
	s_waitcnt vmcnt(17)
	ds_write_b128 v168, v[84:87] offset:26112
	s_waitcnt vmcnt(16)
	ds_write_b128 v169, v[88:91] offset:34816
	v_add_u32_e32 v72, s34, v154
	s_add_i32 s34, s20, 4
	s_waitcnt vmcnt(15)
	s_cmp_lg_u32 s69, 0
	s_cbranch_scc1 .Lev_skip_b
	ds_write_b128 v72, v[92:95]
.Lev_skip_b:
	v_sub_u32_e64 v72, 59, s44 clamp
	s_and_b64 s[20:21], exec, s[38:39]
	v_readfirstlane_b32 s20, v72
	s_cselect_b32 s48, s34, s20
	v_add_u32_e32 v96, s61, v143
	s_lshl_b32 s34, s48, 13
	s_lshl_b32 s49, s48, 14
	ds_read_b128 v[186:189], v96
	s_add_u32 s20, s43, s49
	s_addc_u32 s21, s63, 0
	v_lshl_add_u64 v[76:77], s[20:21], 0, v[120:121]
	global_load_dwordx4 v[72:75], v120, s[20:21]
	v_add_co_u32_e64 v76, s[20:21], s60, v76
	s_waitcnt lgkmcnt(0)
	v_pk_mul_f32 v[118:119], v[118:119], v[188:189]
	v_addc_co_u32_e64 v77, s[20:21], 0, v77, s[20:21]
	v_pk_mul_f32 v[116:117], v[116:117], v[186:187]
	s_add_u32 s20, s64, s49
	v_pk_mul_f32 v[114:115], v[114:115], v[118:119]
	v_pk_mul_f32 v[112:113], v[112:113], v[116:117]
	s_addc_u32 s21, s65, 0
	v_add_u32_e32 v96, 0x1ea00, v185
	v_cvt_pk_bf16_f32 v186, v112, v113
	v_cvt_pk_bf16_f32 v187, v114, v115
	v_pk_mul_f32 v[110:111], v[110:111], v[118:119]
	v_pk_mul_f32 v[108:109], v[108:109], v[116:117]
	v_lshl_add_u64 v[84:85], s[20:21], 0, v[120:121]
	ds_read_b128 v[96:99], v96
	ds_write_b64 v182, v[186:187]
	v_cvt_pk_bf16_f32 v186, v108, v109
	v_cvt_pk_bf16_f32 v187, v110, v111
	v_pk_mul_f32 v[106:107], v[106:107], v[118:119]
	v_pk_mul_f32 v[104:105], v[104:105], v[116:117]
	v_pk_mul_f32 v[102:103], v[102:103], v[118:119]
	v_pk_mul_f32 v[100:101], v[100:101], v[116:117]
	global_load_dwordx4 v[80:83], v[76:77], off
	v_lshl_add_u64 v[88:89], v[146:147], 0, s[34:35]
	global_load_dwordx4 v[76:79], v120, s[20:21]
	v_add_co_u32_e64 v84, s[20:21], s60, v84
	s_lshl_b32 s34, s48, 10
	ds_write_b64 v182, v[186:187] offset:4352
	v_cvt_pk_bf16_f32 v186, v104, v105
	v_cvt_pk_bf16_f32 v187, v106, v107
	v_cvt_pk_bf16_f32 v116, v100, v101
	v_cvt_pk_bf16_f32 v117, v102, v103
	v_addc_co_u32_e64 v85, s[20:21], 0, v85, s[20:21]
	v_lshl_add_u64 v[92:93], v[148:149], 0, s[34:35]
	ds_write_b64 v182, v[186:187] offset:8704
	ds_write_b64 v182, v[116:117] offset:13056
	global_load_dwordx4 v[84:87], v[84:85], off
	v_add_u32_e32 v185, s31, v162
	global_load_dwordx4 v[88:91], v[88:89], off
	v_add_u32_e32 v194, s45, v159
	global_load_dwordx4 v[92:95], v[92:93], off
	s_waitcnt lgkmcnt(0)
	s_barrier
	ds_read_b128 v[218:221], v170 offset:17408
	ds_read_b128 v[222:225], v171
	ds_read_b128 v[226:229], v172
	ds_read_b64_tr_b16 v[230:231], v178 offset:61440
	ds_read_b64_tr_b16 v[232:233], v178 offset:62528
	ds_read_b64_tr_b16 v[234:235], v162
	ds_read_b64_tr_b16 v[236:237], v162 offset:576
	ds_read_b64_tr_b16 v[238:239], v162 offset:32
	ds_read_b64_tr_b16 v[240:241], v162 offset:608
	ds_read_b128 v[242:245], v170 offset:17472
	ds_read_b128 v[246:249], v171 offset:64
	ds_read_b128 v[250:253], v172 offset:64
	s_add_i32 s34, s44, 1
	s_and_b64 s[20:21], exec, s[38:39]
	s_cselect_b32 s20, s34, s47
	s_lshl_b32 s34, s20, 6
	s_add_i32 s47, s47, -2
	v_lshl_add_u64 v[152:153], v[152:153], 0, s[36:37]
	s_waitcnt lgkmcnt(9)
	v_mfma_f32_16x16x32_bf16 v[190:193], v[218:221], v[222:225], 0
	v_mfma_f32_16x16x32_bf16 v[194:197], v[218:221], v[226:229], 0
	ds_read_b64_tr_b16 v[218:219], v178 offset:61440
	ds_read_b64_tr_b16 v[220:221], v178 offset:62528
	ds_read_b64_tr_b16 v[222:223], v162 offset:64
	ds_read_b64_tr_b16 v[224:225], v162 offset:640
	ds_read_b64_tr_b16 v[226:227], v162 offset:96
	ds_read_b64_tr_b16 v[228:229], v162 offset:672
	s_waitcnt lgkmcnt(9)
	v_mfma_f32_16x16x32_bf16 v[112:115], v[230:233], v[234:237], v[112:115]
	v_mfma_f32_16x16x32_bf16 v[108:111], v[230:233], v[238:241], v[108:111]
	ds_read_b128 v[230:233], v170 offset:17536
	ds_read_b128 v[234:237], v171 offset:128
	ds_read_b128 v[238:241], v172 offset:128
	s_waitcnt lgkmcnt(9)
	v_mfma_f32_16x16x32_bf16 v[190:193], v[242:245], v[246:249], v[190:193]
	v_mfma_f32_16x16x32_bf16 v[194:197], v[242:245], v[250:253], v[194:197]
	ds_read_b64_tr_b16 v[242:243], v207
	ds_read_b64_tr_b16 v[244:245], v207 offset:576
	ds_read_b128 v[246:249], v210
	ds_read_b128 v[250:253], v211
	s_waitcnt lgkmcnt(7)
	v_mfma_f32_16x16x32_bf16 v[214:217], v[218:221], v[222:225], v[104:107]
	v_mfma_f32_16x16x32_bf16 v[116:119], v[218:221], v[226:229], v[100:103]
	ds_read_b128 v[218:221], v170 offset:17600
	ds_read_b128 v[222:225], v171 offset:192
	ds_read_b128 v[226:229], v172 offset:192
	s_waitcnt lgkmcnt(7)
	v_mfma_f32_16x16x32_bf16 v[190:193], v[230:233], v[234:237], v[190:193]
	v_mfma_f32_16x16x32_bf16 v[194:197], v[230:233], v[238:241], v[194:197]
	ds_read_b64_tr_b16 v[230:231], v207 offset:4608
	ds_read_b64_tr_b16 v[232:233], v207 offset:5184
	ds_read_b128 v[234:237], v210 offset:64
	ds_read_b128 v[238:241], v211 offset:64
	s_waitcnt lgkmcnt(7)
	v_mfma_f32_16x16x32_bf16 v[198:201], v[242:245], v[246:249], 0
	v_mfma_f32_16x16x32_bf16 v[202:205], v[242:245], v[250:253], 0
	ds_read_b128 v[242:245], v183
	ds_read_b128 v[246:249], v171 offset:44032
	ds_read_b128 v[250:253], v172 offset:44032
	s_waitcnt lgkmcnt(7)
	v_mfma_f32_16x16x32_bf16 v[190:193], v[218:221], v[222:225], v[190:193]
	v_mfma_f32_16x16x32_bf16 v[194:197], v[218:221], v[226:229], v[194:197]
	ds_read_b128 v[218:221], v183 offset:64
	ds_read_b128 v[222:225], v171 offset:44096
	ds_read_b128 v[226:229], v172 offset:44096
	s_waitcnt lgkmcnt(6)
	v_mfma_f32_16x16x32_bf16 v[198:201], v[230:233], v[234:237], v[198:201]
	v_mfma_f32_16x16x32_bf16 v[202:205], v[230:233], v[238:241], v[202:205]
	ds_read_b128 v[230:233], v183 offset:128
	ds_read_b128 v[234:237], v171 offset:44160
	ds_read_b128 v[238:241], v172 offset:44160
	v_cndmask_b32_e32 v190, 0, v190, vcc
	v_cndmask_b32_e64 v191, 0, v191, s[6:7]
	v_cndmask_b32_e64 v192, 0, v192, s[8:9]
	v_cndmask_b32_e64 v193, 0, v193, s[10:11]
	v_cvt_pk_bf16_f32 v190, v190, v191
	v_cvt_pk_bf16_f32 v191, v192, v193
	v_cndmask_b32_e64 v194, 0, v194, s[12:13]
	v_cndmask_b32_e64 v195, 0, v195, s[14:15]
	v_cndmask_b32_e64 v196, 0, v196, s[16:17]
	v_cndmask_b32_e64 v197, 0, v197, s[18:19]
	v_cvt_pk_bf16_f32 v194, v194, v195
	v_cvt_pk_bf16_f32 v195, v196, v197
	ds_write_b64 v175, v[190:191]
	ds_write_b64 v177, v[194:195]
	s_waitcnt lgkmcnt(8)
	v_mfma_f32_16x16x32_bf16 v[198:201], v[242:245], v[246:249], v[198:201]
	v_mfma_f32_16x16x32_bf16 v[202:205], v[242:245], v[250:253], v[202:205]
	ds_read_b128 v[242:245], v183 offset:192
	ds_read_b128 v[246:249], v171 offset:44224
	ds_read_b128 v[250:253], v172 offset:44224
	s_waitcnt lgkmcnt(8)
	v_mfma_f32_16x16x32_bf16 v[198:201], v[218:221], v[222:225], v[198:201]
	v_mfma_f32_16x16x32_bf16 v[202:205], v[218:221], v[226:229], v[202:205]
	ds_read_b64_tr_b16 v[218:219], v181 offset:8704
	ds_read_b64_tr_b16 v[220:221], v181 offset:9792
	ds_read_b64_tr_b16 v[222:223], v162 offset:4608
	ds_read_b64_tr_b16 v[224:225], v162 offset:5184
	ds_read_b64_tr_b16 v[226:227], v162 offset:4640
	ds_read_b64_tr_b16 v[228:229], v162 offset:5216
	s_waitcnt lgkmcnt(11)
	v_mfma_f32_16x16x32_bf16 v[198:201], v[230:233], v[234:237], v[198:201]
	v_mfma_f32_16x16x32_bf16 v[202:205], v[230:233], v[238:241], v[202:205]
	ds_read_b64_tr_b16 v[230:231], v181 offset:8704
	ds_read_b64_tr_b16 v[232:233], v181 offset:9792
	ds_read_b64_tr_b16 v[234:235], v162 offset:4672
	ds_read_b64_tr_b16 v[236:237], v162 offset:5248
	ds_read_b64_tr_b16 v[238:239], v162 offset:4704
	ds_read_b64_tr_b16 v[240:241], v162 offset:5280
	s_waitcnt lgkmcnt(12)
	v_mfma_f32_16x16x32_bf16 v[198:201], v[242:245], v[246:249], v[198:201]
	v_mfma_f32_16x16x32_bf16 v[202:205], v[242:245], v[250:253], v[202:205]
	s_waitcnt lgkmcnt(6)
	v_mfma_f32_16x16x32_bf16 v[100:103], v[218:221], v[222:225], v[112:115]
	v_mfma_f32_16x16x32_bf16 v[104:107], v[218:221], v[226:229], v[108:111]
	s_nop 3
	v_cvt_pk_bf16_f32 v198, v198, v199
	v_cvt_pk_bf16_f32 v199, v200, v201
	v_add_u32_e32 v254, s34, v173
	v_mad_u64_u32 v[254:255], s[20:21], v254, s42, 0
	v_lshl_add_u64 v[254:255], v[254:255], 1, v[150:151]
	v_cvt_pk_bf16_f32 v202, v202, v203
	v_cvt_pk_bf16_f32 v203, v204, v205
	global_store_dwordx2 v[254:255], v[198:199], off
	v_add_u32_e32 v254, s34, v179
	v_mad_u64_u32 v[254:255], s[20:21], v254, s42, 0
	v_lshl_add_u64 v[254:255], v[254:255], 1, v[150:151]
	global_store_dwordx2 v[254:255], v[202:203], off
	s_waitcnt lgkmcnt(0)
	v_mfma_f32_16x16x32_bf16 v[108:111], v[230:233], v[234:237], v[214:217]
	v_mfma_f32_16x16x32_bf16 v[112:115], v[230:233], v[238:241], v[116:119]
	s_add_i32 s20, s44, 2
	s_cmp_lt_u32 s44, 62
	s_mov_b32 s44, s20
	s_waitcnt lgkmcnt(0)
	s_barrier
	s_cbranch_scc1 .LBB0_350
	s_add_i32 s30, s30, s28
	v_lshl_add_u64 v[140:141], v[140:141], 0, s[26:27]
	s_cmpk_lt_i32 s30, 0x100
	v_add_u32_e32 v165, s29, v165
	s_cbranch_scc1 .LBB0_344
